# xcd barriers: buffer_wbl2 issued right after the arrival atomic (write-back overlaps the atomic round trip for every workgroup)
# baseline (speedup 1.0000x reference)
; __device__ __forceinline__ unsigned xb_ld(unsigned* p)              { return __hip_atomic_load(p, __ATOMIC_RELAXED, __HIP_MEMORY_SCOPE_AGENT); }
; __device__ __forceinline__ unsigned xb_add(unsigned* p, unsigned v) { return __hip_atomic_fetch_add(p, v, __ATOMIC_RELAXED, __HIP_MEMORY_SCOPE_AGENT); }
; #define XB_SPIN(cond, bar) do { unsigned _sp = 0; while (cond) { __builtin_amdgcn_s_sleep(1); \
;     if ((++_sp & 255u) == 0u) { if (xb_ld(&(bar)[XB_TMO])) break; if (_sp > XB_SPIN_CAP) { atomicAdd(&(bar)[XB_TMO], 1u); break; } } } } while (0)
; __device__ __forceinline__ void xcd_barrier(const XcdBarrier& b) {
;     ...
;     if (threadIdx.x == 0) {
;         unsigned* bar = b.bar;
;         __builtin_amdgcn_s_waitcnt(0);
;         unsigned nloc = b.st[0], nx = b.st[1];
;         if (nloc == 0u) { xcd_barrier_complete(bar, b.x, nloc, nx); b.st[0] = nloc; b.st[1] = nx; }
;         const unsigned old = xb_add(&bar[XB_XSUB(b.x)], 1u);
;         const unsigned gen = old / nloc;
;         if (old + 1u == (gen + 1u) * nloc) {
;             __builtin_amdgcn_fence(__ATOMIC_RELEASE, "agent");
;             asm volatile("s_waitcnt vmcnt(0)" ::: "memory");
;             const unsigned og = xb_add(&bar[XB_TOP], 1u);
;             const unsigned tg = og / nx;
;             if (og + 1u == (tg + 1u) * nx) xb_add(&bar[XB_TOPGEN], 1u);
;             else XB_SPIN(xb_ld(&bar[XB_TOPGEN]) == tg, bar);
;             __builtin_amdgcn_fence(__ATOMIC_ACQUIRE, "agent");
;             xb_add(&bar[XB_XGEN(b.x)], 1u);
;             asm volatile("s_waitcnt vmcnt(0)" ::: "memory");
;         } else {
;             XB_SPIN(xb_ld(&bar[XB_XGEN(b.x)]) == gen, bar);
.LBB0_96:
	v_readlane_b32 s3, v254, 45
	s_lshl_b32 s3, s3, 8
	v_readlane_b32 s6, v254, 43
	v_readlane_b32 s7, v254, 44
	s_add_u32 s6, s6, s3
	s_addc_u32 s7, s7, 0
	v_mov_b32_e32 v1, 0x1000
	v_mov_b32_e32 v3, 1
	v_sub_u32_e32 v4, 0, v2
	global_atomic_add v3, v1, v3, s[6:7] offset:1024 sc0
	buffer_wbl2 sc1
	v_cvt_f32_u32_e32 v1, v2
	v_rcp_iflag_f32_e32 v1, v1
	s_nop 0
	v_mul_f32_e32 v1, 0x4f7ffffe, v1
	v_cvt_u32_f32_e32 v1, v1
	v_mul_lo_u32 v4, v4, v1
	v_mul_hi_u32 v4, v1, v4
	v_add_u32_e32 v1, v1, v4
	s_waitcnt vmcnt(0)
	v_mul_hi_u32 v1, v3, v1
	v_mul_lo_u32 v4, v1, v2
	v_sub_u32_e32 v4, v3, v4
	v_add_u32_e32 v5, 1, v1
	v_cmp_ge_u32_e32 vcc, v4, v2
	v_add_u32_e32 v3, 1, v3
	s_nop 0
	v_cndmask_b32_e32 v1, v1, v5, vcc
	v_sub_u32_e32 v5, v4, v2
	v_cndmask_b32_e32 v4, v4, v5, vcc
	v_add_u32_e32 v5, 1, v1
	v_cmp_ge_u32_e32 vcc, v4, v2
	s_nop 1
	v_cndmask_b32_e32 v1, v1, v5, vcc
	v_mul_lo_u32 v4, v2, v1
	v_add_u32_e32 v2, v4, v2
	v_cmp_ne_u32_e32 vcc, v3, v2
	s_and_saveexec_b64 s[8:9], vcc
	s_xor_b64 s[8:9], exec, s[8:9]
	s_cbranch_execz .LBB0_110
	s_waitcnt lgkmcnt(0)
	v_mov_b32_e32 v1, 0
	s_add_u32 s14, s78, 0x193e3500
	s_addc_u32 s15, s79, 0
	v_mov_b32_e32 v0, 0
	global_load_dword v0, v0, s[14:15] sc1
	s_waitcnt vmcnt(0)
	v_cmp_eq_u32_e32 vcc, v0, v1
	s_and_saveexec_b64 s[10:11], vcc
	s_cbranch_execz .LBB0_109
	s_add_u32 s12, s78, 0x193e0200
	s_addc_u32 s13, s79, 0
	s_mov_b32 s3, 1
	s_mov_b64 s[16:17], 0
	v_mov_b32_e32 v0, 0
	s_branch .LBB0_100

; __device__ __forceinline__ unsigned xb_ld(unsigned* p)              { return __hip_atomic_load(p, __ATOMIC_RELAXED, __HIP_MEMORY_SCOPE_AGENT); }
; __device__ __forceinline__ unsigned xb_add(unsigned* p, unsigned v) { return __hip_atomic_fetch_add(p, v, __ATOMIC_RELAXED, __HIP_MEMORY_SCOPE_AGENT); }
; #define XB_SPIN(cond, bar) do { unsigned _sp = 0; while (cond) { __builtin_amdgcn_s_sleep(1); \
;     if ((++_sp & 255u) == 0u) { if (xb_ld(&(bar)[XB_TMO])) break; if (_sp > XB_SPIN_CAP) { atomicAdd(&(bar)[XB_TMO], 1u); break; } } } } while (0)
; __device__ __forceinline__ void xcd_barrier(const XcdBarrier& b) {
;     ...
;     if (threadIdx.x == 0) {
;         unsigned* bar = b.bar;
;         __builtin_amdgcn_s_waitcnt(0);
;         unsigned nloc = b.st[0], nx = b.st[1];
;         if (nloc == 0u) { xcd_barrier_complete(bar, b.x, nloc, nx); b.st[0] = nloc; b.st[1] = nx; }
;         const unsigned old = xb_add(&bar[XB_XSUB(b.x)], 1u);
;         const unsigned gen = old / nloc;
;         if (old + 1u == (gen + 1u) * nloc) {
;             __builtin_amdgcn_fence(__ATOMIC_RELEASE, "agent");
;             asm volatile("s_waitcnt vmcnt(0)" ::: "memory");
;             const unsigned og = xb_add(&bar[XB_TOP], 1u);
;             const unsigned tg = og / nx;
;             if (og + 1u == (tg + 1u) * nx) xb_add(&bar[XB_TOPGEN], 1u);
;             else XB_SPIN(xb_ld(&bar[XB_TOPGEN]) == tg, bar);
;             __builtin_amdgcn_fence(__ATOMIC_ACQUIRE, "agent");
;             xb_add(&bar[XB_XGEN(b.x)], 1u);
;             asm volatile("s_waitcnt vmcnt(0)" ::: "memory");
;         } else {
;             XB_SPIN(xb_ld(&bar[XB_XGEN(b.x)]) == gen, bar);
.LBB0_241:
	v_readlane_b32 s3, v254, 45
	s_lshl_b32 s3, s3, 8
	v_readlane_b32 s6, v254, 43
	v_readlane_b32 s7, v254, 44
	s_add_u32 s6, s6, s3
	s_addc_u32 s7, s7, 0
	v_mov_b32_e32 v1, 0x1000
	v_mov_b32_e32 v3, 1
	v_sub_u32_e32 v4, 0, v2
	global_atomic_add v3, v1, v3, s[6:7] offset:1024 sc0
	buffer_wbl2 sc1
	v_cvt_f32_u32_e32 v1, v2
	v_rcp_iflag_f32_e32 v1, v1
	s_nop 0
	v_mul_f32_e32 v1, 0x4f7ffffe, v1
	v_cvt_u32_f32_e32 v1, v1
	v_mul_lo_u32 v4, v4, v1
	v_mul_hi_u32 v4, v1, v4
	v_add_u32_e32 v1, v1, v4
	s_waitcnt vmcnt(0)
	v_mul_hi_u32 v1, v3, v1
	v_mul_lo_u32 v4, v1, v2
	v_sub_u32_e32 v4, v3, v4
	v_add_u32_e32 v5, 1, v1
	v_cmp_ge_u32_e32 vcc, v4, v2
	v_add_u32_e32 v3, 1, v3
	s_nop 0
	v_cndmask_b32_e32 v1, v1, v5, vcc
	v_sub_u32_e32 v5, v4, v2
	v_cndmask_b32_e32 v4, v4, v5, vcc
	v_add_u32_e32 v5, 1, v1
	v_cmp_ge_u32_e32 vcc, v4, v2
	s_nop 1
	v_cndmask_b32_e32 v1, v1, v5, vcc
	v_mul_lo_u32 v4, v2, v1
	v_add_u32_e32 v2, v4, v2
	v_cmp_ne_u32_e32 vcc, v3, v2
	s_and_saveexec_b64 s[8:9], vcc
	s_xor_b64 s[8:9], exec, s[8:9]
	s_cbranch_execz .LBB0_255
	s_waitcnt lgkmcnt(0)
	v_mov_b32_e32 v1, 1
	s_add_u32 s14, s78, 0x193e3500
	s_addc_u32 s15, s79, 0
	v_mov_b32_e32 v0, 0
	global_load_dword v0, v0, s[14:15] sc1
	s_waitcnt vmcnt(0)
	v_cmp_eq_u32_e32 vcc, v0, v1
	s_and_saveexec_b64 s[10:11], vcc
	s_cbranch_execz .LBB0_254
	s_add_u32 s12, s78, 0x193e0200
	s_addc_u32 s13, s79, 0
	s_mov_b32 s3, 1
	s_mov_b64 s[16:17], 0
	v_mov_b32_e32 v0, 0
	s_branch .LBB0_245

; __device__ __forceinline__ unsigned xb_ld(unsigned* p)              { return __hip_atomic_load(p, __ATOMIC_RELAXED, __HIP_MEMORY_SCOPE_AGENT); }
; __device__ __forceinline__ unsigned xb_add(unsigned* p, unsigned v) { return __hip_atomic_fetch_add(p, v, __ATOMIC_RELAXED, __HIP_MEMORY_SCOPE_AGENT); }
; #define XB_SPIN(cond, bar) do { unsigned _sp = 0; while (cond) { __builtin_amdgcn_s_sleep(1); \
;     if ((++_sp & 255u) == 0u) { if (xb_ld(&(bar)[XB_TMO])) break; if (_sp > XB_SPIN_CAP) { atomicAdd(&(bar)[XB_TMO], 1u); break; } } } } while (0)
; __device__ __forceinline__ void xcd_barrier(const XcdBarrier& b) {
;     ...
;     if (threadIdx.x == 0) {
;         unsigned* bar = b.bar;
;         __builtin_amdgcn_s_waitcnt(0);
;         unsigned nloc = b.st[0], nx = b.st[1];
;         if (nloc == 0u) { xcd_barrier_complete(bar, b.x, nloc, nx); b.st[0] = nloc; b.st[1] = nx; }
;         const unsigned old = xb_add(&bar[XB_XSUB(b.x)], 1u);
;         const unsigned gen = old / nloc;
;         if (old + 1u == (gen + 1u) * nloc) {
;             __builtin_amdgcn_fence(__ATOMIC_RELEASE, "agent");
;             asm volatile("s_waitcnt vmcnt(0)" ::: "memory");
;             const unsigned og = xb_add(&bar[XB_TOP], 1u);
;             const unsigned tg = og / nx;
;             if (og + 1u == (tg + 1u) * nx) xb_add(&bar[XB_TOPGEN], 1u);
;             else XB_SPIN(xb_ld(&bar[XB_TOPGEN]) == tg, bar);
;             __builtin_amdgcn_fence(__ATOMIC_ACQUIRE, "agent");
;             xb_add(&bar[XB_XGEN(b.x)], 1u);
;             asm volatile("s_waitcnt vmcnt(0)" ::: "memory");
;         } else {
;             XB_SPIN(xb_ld(&bar[XB_XGEN(b.x)]) == gen, bar);
.LBB0_337:
	v_readlane_b32 s3, v254, 45
	s_lshl_b32 s3, s3, 8
	v_readlane_b32 s6, v254, 43
	v_readlane_b32 s7, v254, 44
	s_add_u32 s6, s6, s3
	s_addc_u32 s7, s7, 0
	v_mov_b32_e32 v1, 0x1000
	v_mov_b32_e32 v3, 1
	v_sub_u32_e32 v4, 0, v2
	global_atomic_add v3, v1, v3, s[6:7] offset:1024 sc0
	buffer_wbl2 sc1
	v_cvt_f32_u32_e32 v1, v2
	v_rcp_iflag_f32_e32 v1, v1
	s_nop 0
	v_mul_f32_e32 v1, 0x4f7ffffe, v1
	v_cvt_u32_f32_e32 v1, v1
	v_mul_lo_u32 v4, v4, v1
	v_mul_hi_u32 v4, v1, v4
	v_add_u32_e32 v1, v1, v4
	s_waitcnt vmcnt(0)
	v_mul_hi_u32 v1, v3, v1
	v_mul_lo_u32 v4, v1, v2
	v_sub_u32_e32 v4, v3, v4
	v_add_u32_e32 v5, 1, v1
	v_cmp_ge_u32_e32 vcc, v4, v2
	v_add_u32_e32 v3, 1, v3
	s_nop 0
	v_cndmask_b32_e32 v1, v1, v5, vcc
	v_sub_u32_e32 v5, v4, v2
	v_cndmask_b32_e32 v4, v4, v5, vcc
	v_add_u32_e32 v5, 1, v1
	v_cmp_ge_u32_e32 vcc, v4, v2
	s_nop 1
	v_cndmask_b32_e32 v1, v1, v5, vcc
	v_mul_lo_u32 v4, v2, v1
	v_add_u32_e32 v2, v4, v2
	v_cmp_ne_u32_e32 vcc, v3, v2
	s_and_saveexec_b64 s[8:9], vcc
	s_xor_b64 s[8:9], exec, s[8:9]
	s_cbranch_execz .LBB0_351
	s_waitcnt lgkmcnt(0)
	v_mov_b32_e32 v1, 2
	s_add_u32 s14, s78, 0x193e3500
	s_addc_u32 s15, s79, 0
	v_mov_b32_e32 v0, 0
	global_load_dword v0, v0, s[14:15] sc1
	s_waitcnt vmcnt(0)
	v_cmp_eq_u32_e32 vcc, v0, v1
	s_and_saveexec_b64 s[10:11], vcc
	s_cbranch_execz .LBB0_350
	s_add_u32 s12, s78, 0x193e0200
	s_addc_u32 s13, s79, 0
	s_mov_b32 s3, 1
	s_mov_b64 s[16:17], 0
	v_mov_b32_e32 v0, 0
	s_branch .LBB0_341

; __device__ __forceinline__ unsigned xb_ld(unsigned* p)              { return __hip_atomic_load(p, __ATOMIC_RELAXED, __HIP_MEMORY_SCOPE_AGENT); }
; __device__ __forceinline__ unsigned xb_add(unsigned* p, unsigned v) { return __hip_atomic_fetch_add(p, v, __ATOMIC_RELAXED, __HIP_MEMORY_SCOPE_AGENT); }
; #define XB_SPIN(cond, bar) do { unsigned _sp = 0; while (cond) { __builtin_amdgcn_s_sleep(1); \
;     if ((++_sp & 255u) == 0u) { if (xb_ld(&(bar)[XB_TMO])) break; if (_sp > XB_SPIN_CAP) { atomicAdd(&(bar)[XB_TMO], 1u); break; } } } } while (0)
; __device__ __forceinline__ void xcd_barrier(const XcdBarrier& b) {
;     ...
;     if (threadIdx.x == 0) {
;         unsigned* bar = b.bar;
;         __builtin_amdgcn_s_waitcnt(0);
;         unsigned nloc = b.st[0], nx = b.st[1];
;         if (nloc == 0u) { xcd_barrier_complete(bar, b.x, nloc, nx); b.st[0] = nloc; b.st[1] = nx; }
;         const unsigned old = xb_add(&bar[XB_XSUB(b.x)], 1u);
;         const unsigned gen = old / nloc;
;         if (old + 1u == (gen + 1u) * nloc) {
;             __builtin_amdgcn_fence(__ATOMIC_RELEASE, "agent");
;             asm volatile("s_waitcnt vmcnt(0)" ::: "memory");
;             const unsigned og = xb_add(&bar[XB_TOP], 1u);
;             const unsigned tg = og / nx;
;             if (og + 1u == (tg + 1u) * nx) xb_add(&bar[XB_TOPGEN], 1u);
;             else XB_SPIN(xb_ld(&bar[XB_TOPGEN]) == tg, bar);
;             __builtin_amdgcn_fence(__ATOMIC_ACQUIRE, "agent");
;             xb_add(&bar[XB_XGEN(b.x)], 1u);
;             asm volatile("s_waitcnt vmcnt(0)" ::: "memory");
;         } else {
;             XB_SPIN(xb_ld(&bar[XB_XGEN(b.x)]) == gen, bar);
.LBB0_443:
	v_readlane_b32 s3, v254, 45
	s_lshl_b32 s3, s3, 8
	v_readlane_b32 s6, v254, 43
	v_readlane_b32 s7, v254, 44
	s_add_u32 s6, s6, s3
	s_addc_u32 s7, s7, 0
	v_mov_b32_e32 v1, 0x1000
	v_mov_b32_e32 v3, 1
	v_sub_u32_e32 v4, 0, v2
	global_atomic_add v3, v1, v3, s[6:7] offset:1024 sc0
	buffer_wbl2 sc1
	v_cvt_f32_u32_e32 v1, v2
	v_rcp_iflag_f32_e32 v1, v1
	s_nop 0
	v_mul_f32_e32 v1, 0x4f7ffffe, v1
	v_cvt_u32_f32_e32 v1, v1
	v_mul_lo_u32 v4, v4, v1
	v_mul_hi_u32 v4, v1, v4
	v_add_u32_e32 v1, v1, v4
	s_waitcnt vmcnt(0)
	v_mul_hi_u32 v1, v3, v1
	v_mul_lo_u32 v4, v1, v2
	v_sub_u32_e32 v4, v3, v4
	v_add_u32_e32 v5, 1, v1
	v_cmp_ge_u32_e32 vcc, v4, v2
	v_add_u32_e32 v3, 1, v3
	s_nop 0
	v_cndmask_b32_e32 v1, v1, v5, vcc
	v_sub_u32_e32 v5, v4, v2
	v_cndmask_b32_e32 v4, v4, v5, vcc
	v_add_u32_e32 v5, 1, v1
	v_cmp_ge_u32_e32 vcc, v4, v2
	s_nop 1
	v_cndmask_b32_e32 v1, v1, v5, vcc
	v_mul_lo_u32 v4, v2, v1
	v_add_u32_e32 v2, v4, v2
	v_cmp_ne_u32_e32 vcc, v3, v2
	s_and_saveexec_b64 s[8:9], vcc
	s_xor_b64 s[8:9], exec, s[8:9]
	s_cbranch_execz .LBB0_457
	s_waitcnt lgkmcnt(0)
	v_mov_b32_e32 v1, 3
	s_add_u32 s14, s78, 0x193e3500
	s_addc_u32 s15, s79, 0
	v_mov_b32_e32 v0, 0
	global_load_dword v0, v0, s[14:15] sc1
	s_waitcnt vmcnt(0)
	v_cmp_eq_u32_e32 vcc, v0, v1
	s_and_saveexec_b64 s[10:11], vcc
	s_cbranch_execz .LBB0_456
	s_add_u32 s12, s78, 0x193e0200
	s_addc_u32 s13, s79, 0
	s_mov_b32 s3, 1
	s_mov_b64 s[16:17], 0
	v_mov_b32_e32 v0, 0
	s_branch .LBB0_447

; __device__ __forceinline__ unsigned xb_ld(unsigned* p)              { return __hip_atomic_load(p, __ATOMIC_RELAXED, __HIP_MEMORY_SCOPE_AGENT); }
; __device__ __forceinline__ unsigned xb_add(unsigned* p, unsigned v) { return __hip_atomic_fetch_add(p, v, __ATOMIC_RELAXED, __HIP_MEMORY_SCOPE_AGENT); }
; #define XB_SPIN(cond, bar) do { unsigned _sp = 0; while (cond) { __builtin_amdgcn_s_sleep(1); \
;     if ((++_sp & 255u) == 0u) { if (xb_ld(&(bar)[XB_TMO])) break; if (_sp > XB_SPIN_CAP) { atomicAdd(&(bar)[XB_TMO], 1u); break; } } } } while (0)
; __device__ __forceinline__ void xcd_barrier(const XcdBarrier& b) {
;     ...
;     if (threadIdx.x == 0) {
;         unsigned* bar = b.bar;
;         __builtin_amdgcn_s_waitcnt(0);
;         unsigned nloc = b.st[0], nx = b.st[1];
;         if (nloc == 0u) { xcd_barrier_complete(bar, b.x, nloc, nx); b.st[0] = nloc; b.st[1] = nx; }
;         const unsigned old = xb_add(&bar[XB_XSUB(b.x)], 1u);
;         const unsigned gen = old / nloc;
;         if (old + 1u == (gen + 1u) * nloc) {
;             __builtin_amdgcn_fence(__ATOMIC_RELEASE, "agent");
;             asm volatile("s_waitcnt vmcnt(0)" ::: "memory");
;             const unsigned og = xb_add(&bar[XB_TOP], 1u);
;             const unsigned tg = og / nx;
;             if (og + 1u == (tg + 1u) * nx) xb_add(&bar[XB_TOPGEN], 1u);
;             else XB_SPIN(xb_ld(&bar[XB_TOPGEN]) == tg, bar);
;             __builtin_amdgcn_fence(__ATOMIC_ACQUIRE, "agent");
;             xb_add(&bar[XB_XGEN(b.x)], 1u);
;             asm volatile("s_waitcnt vmcnt(0)" ::: "memory");
;         } else {
;             XB_SPIN(xb_ld(&bar[XB_XGEN(b.x)]) == gen, bar);
.LBB0_517:
	v_readlane_b32 s3, v254, 45
	s_lshl_b32 s3, s3, 8
	v_readlane_b32 s6, v254, 43
	v_readlane_b32 s7, v254, 44
	s_add_u32 s6, s6, s3
	s_addc_u32 s7, s7, 0
	v_mov_b32_e32 v1, 0x1000
	v_mov_b32_e32 v3, 1
	v_sub_u32_e32 v4, 0, v2
	global_atomic_add v3, v1, v3, s[6:7] offset:1024 sc0
	buffer_wbl2 sc1
	v_cvt_f32_u32_e32 v1, v2
	v_rcp_iflag_f32_e32 v1, v1
	s_nop 0
	v_mul_f32_e32 v1, 0x4f7ffffe, v1
	v_cvt_u32_f32_e32 v1, v1
	v_mul_lo_u32 v4, v4, v1
	v_mul_hi_u32 v4, v1, v4
	v_add_u32_e32 v1, v1, v4
	s_waitcnt vmcnt(0)
	v_mul_hi_u32 v1, v3, v1
	v_mul_lo_u32 v4, v1, v2
	v_sub_u32_e32 v4, v3, v4
	v_add_u32_e32 v5, 1, v1
	v_cmp_ge_u32_e32 vcc, v4, v2
	v_add_u32_e32 v3, 1, v3
	s_nop 0
	v_cndmask_b32_e32 v1, v1, v5, vcc
	v_sub_u32_e32 v5, v4, v2
	v_cndmask_b32_e32 v4, v4, v5, vcc
	v_add_u32_e32 v5, 1, v1
	v_cmp_ge_u32_e32 vcc, v4, v2
	s_nop 1
	v_cndmask_b32_e32 v1, v1, v5, vcc
	v_mul_lo_u32 v4, v2, v1
	v_add_u32_e32 v2, v4, v2
	v_cmp_ne_u32_e32 vcc, v3, v2
	s_and_saveexec_b64 s[8:9], vcc
	s_xor_b64 s[8:9], exec, s[8:9]
	s_cbranch_execz .LBB0_531
	s_waitcnt lgkmcnt(0)
	v_mov_b32_e32 v1, 4
	s_add_u32 s14, s78, 0x193e3500
	s_addc_u32 s15, s79, 0
	v_mov_b32_e32 v0, 0
	global_load_dword v0, v0, s[14:15] sc1
	s_waitcnt vmcnt(0)
	v_cmp_eq_u32_e32 vcc, v0, v1
	s_and_saveexec_b64 s[10:11], vcc
	s_cbranch_execz .LBB0_530
	s_add_u32 s12, s78, 0x193e0200
	s_addc_u32 s13, s79, 0
	s_mov_b32 s3, 1
	s_mov_b64 s[16:17], 0
	v_mov_b32_e32 v0, 0
	s_branch .LBB0_521

; __device__ __forceinline__ unsigned xb_ld(unsigned* p)              { return __hip_atomic_load(p, __ATOMIC_RELAXED, __HIP_MEMORY_SCOPE_AGENT); }
; __device__ __forceinline__ unsigned xb_add(unsigned* p, unsigned v) { return __hip_atomic_fetch_add(p, v, __ATOMIC_RELAXED, __HIP_MEMORY_SCOPE_AGENT); }
; #define XB_SPIN(cond, bar) do { unsigned _sp = 0; while (cond) { __builtin_amdgcn_s_sleep(1); \
;     if ((++_sp & 255u) == 0u) { if (xb_ld(&(bar)[XB_TMO])) break; if (_sp > XB_SPIN_CAP) { atomicAdd(&(bar)[XB_TMO], 1u); break; } } } } while (0)
; __device__ __forceinline__ void xcd_barrier(const XcdBarrier& b) {
;     ...
;     if (threadIdx.x == 0) {
;         unsigned* bar = b.bar;
;         __builtin_amdgcn_s_waitcnt(0);
;         unsigned nloc = b.st[0], nx = b.st[1];
;         if (nloc == 0u) { xcd_barrier_complete(bar, b.x, nloc, nx); b.st[0] = nloc; b.st[1] = nx; }
;         const unsigned old = xb_add(&bar[XB_XSUB(b.x)], 1u);
;         const unsigned gen = old / nloc;
;         if (old + 1u == (gen + 1u) * nloc) {
;             __builtin_amdgcn_fence(__ATOMIC_RELEASE, "agent");
;             asm volatile("s_waitcnt vmcnt(0)" ::: "memory");
;             const unsigned og = xb_add(&bar[XB_TOP], 1u);
;             const unsigned tg = og / nx;
;             if (og + 1u == (tg + 1u) * nx) xb_add(&bar[XB_TOPGEN], 1u);
;             else XB_SPIN(xb_ld(&bar[XB_TOPGEN]) == tg, bar);
;             __builtin_amdgcn_fence(__ATOMIC_ACQUIRE, "agent");
;             xb_add(&bar[XB_XGEN(b.x)], 1u);
;             asm volatile("s_waitcnt vmcnt(0)" ::: "memory");
;         } else {
;             XB_SPIN(xb_ld(&bar[XB_XGEN(b.x)]) == gen, bar);
.LBB0_577:
	v_readlane_b32 s3, v254, 45
	s_lshl_b32 s3, s3, 8
	v_readlane_b32 s6, v254, 43
	v_readlane_b32 s7, v254, 44
	s_add_u32 s6, s6, s3
	s_addc_u32 s7, s7, 0
	v_mov_b32_e32 v1, 0x1000
	v_mov_b32_e32 v3, 1
	v_sub_u32_e32 v4, 0, v2
	global_atomic_add v3, v1, v3, s[6:7] offset:1024 sc0
	buffer_wbl2 sc1
	v_cvt_f32_u32_e32 v1, v2
	v_rcp_iflag_f32_e32 v1, v1
	s_nop 0
	v_mul_f32_e32 v1, 0x4f7ffffe, v1
	v_cvt_u32_f32_e32 v1, v1
	v_mul_lo_u32 v4, v4, v1
	v_mul_hi_u32 v4, v1, v4
	v_add_u32_e32 v1, v1, v4
	s_waitcnt vmcnt(0)
	v_mul_hi_u32 v1, v3, v1
	v_mul_lo_u32 v4, v1, v2
	v_sub_u32_e32 v4, v3, v4
	v_add_u32_e32 v5, 1, v1
	v_cmp_ge_u32_e32 vcc, v4, v2
	v_add_u32_e32 v3, 1, v3
	s_nop 0
	v_cndmask_b32_e32 v1, v1, v5, vcc
	v_sub_u32_e32 v5, v4, v2
	v_cndmask_b32_e32 v4, v4, v5, vcc
	v_add_u32_e32 v5, 1, v1
	v_cmp_ge_u32_e32 vcc, v4, v2
	s_nop 1
	v_cndmask_b32_e32 v1, v1, v5, vcc
	v_mul_lo_u32 v4, v2, v1
	v_add_u32_e32 v2, v4, v2
	v_cmp_ne_u32_e32 vcc, v3, v2
	s_and_saveexec_b64 s[8:9], vcc
	s_xor_b64 s[8:9], exec, s[8:9]
	s_cbranch_execz .LBB0_591
	s_waitcnt lgkmcnt(0)
	v_mov_b32_e32 v1, 5
	s_add_u32 s14, s78, 0x193e3500
	s_addc_u32 s15, s79, 0
	v_mov_b32_e32 v0, 0
	global_load_dword v0, v0, s[14:15] sc1
	s_waitcnt vmcnt(0)
	v_cmp_eq_u32_e32 vcc, v0, v1
	s_and_saveexec_b64 s[10:11], vcc
	s_cbranch_execz .LBB0_590
	s_add_u32 s12, s78, 0x193e0200
	s_addc_u32 s13, s79, 0
	s_mov_b32 s3, 1
	s_mov_b64 s[16:17], 0
	v_mov_b32_e32 v0, 0
	s_branch .LBB0_581
